# HGRN2 elementwise waves: segment prefix by DPP + lane swaps (no LDS round trip), next chunk's k-side decay chain computed under the LDS-write drain before the barrier; split 17:15
# speedup vs baseline: 1.0862x; 1.0025x over previous
.LBB0_268:
	s_add_u32 s48, s98, 0xd900000
	s_addc_u32 s49, s99, 0
	s_add_u32 s76, s98, 0xfb00000
	s_addc_u32 s77, s99, 0
	s_cmp_lt_i32 s4, 3
	s_cselect_b64 s[0:1], -1, 0
	s_cmp_gt_i32 s5, 2
	s_cselect_b64 s[2:3], -1, 0
	s_and_b64 s[0:1], s[0:1], s[2:3]
	s_andn2_b64 vcc, exec, s[0:1]
	s_cbranch_vccnz .LBB0_518
	v_readlane_b32 s2, v250, 3
	s_and_b32 s0, s2, 16
	s_bitcmp1_b32 s2, 4
	s_cselect_b64 s[4:5], -1, 0
	s_ashr_i32 s1, s2, 1
	s_and_b32 s1, s1, -16
	s_and_b32 s2, s2, 15
	v_writelane_b32 v250, s4, 16
	s_or_b32 s1, s1, s2
	v_mov_b32_e32 v1, v0
	v_writelane_b32 v250, s5, 17
	s_lshl_b32 s4, s1, 5
	s_or_b32 s5, s4, 17
	s_cmp_eq_u32 s0, 0
	v_writelane_b32 v250, s1, 18
	s_cselect_b64 s[0:1], -1, 0
	s_and_b64 s[2:3], s[0:1], exec
	s_cselect_b32 s33, s4, s5
	s_ashr_i32 s2, s33, 10
	s_ashr_i32 s3, s2, 31
	s_lshl_b32 s4, s33, 5
	s_lshl_b64 s[2:3], s[2:3], 12
	s_and_b32 s10, s4, 0xfc0
	s_or_b32 s2, s2, s10
	v_ashrrev_i32_e32 v8, 3, v1
	v_lshlrev_b32_e32 v2, 3, v1
	v_ashrrev_i32_e32 v9, 31, v8
	v_and_b32_e32 v7, 56, v2
	v_lshl_add_u64 v[2:3], s[2:3], 0, v[8:9]
	s_movk_i32 s6, 0x2600
	v_mov_b64_e32 v[4:5], s[64:65]
	v_mad_u64_u32 v[4:5], s[4:5], v2, s6, v[4:5]
	v_mov_b32_e32 v6, 0
	v_mad_i32_i24 v5, v3, s6, v5
	v_lshlrev_b32_e32 v46, 1, v7
	v_mov_b32_e32 v47, v6
	v_lshl_add_u64 v[26:27], v[4:5], 0, v[46:47]
	s_and_b32 s8, s33, 1
	s_lshl_b32 s8, s8, 7
	s_mov_b32 s9, 0
	v_lshl_add_u64 v[26:27], v[26:27], 0, s[8:9]
	v_add_co_u32_e32 v2, vcc, 0x1000, v26
	v_add_u32_e32 v7, s10, v8
	s_nop 0
	v_addc_co_u32_e32 v3, vcc, 0, v27, vcc
	global_load_dwordx4 v[2:5], v[2:3], off
	v_cmp_lt_i32_e64 s[6:7], 0, v7
	v_mov_b32_e32 v10, 0
	v_mov_b32_e32 v11, 0
	v_mov_b32_e32 v12, 0
	v_mov_b32_e32 v13, 0
	s_and_saveexec_b64 s[4:5], s[6:7]
	s_cbranch_execz .LBB0_271
	v_add_co_u32_e32 v8, vcc, 0xfffff000, v26
	s_nop 1
	v_addc_co_u32_e32 v9, vcc, -1, v27, vcc
	global_load_dwordx4 v[10:13], v[8:9], off offset:-1536

.LBB0_293:
	s_or_b64 exec, exec, s[4:5]
	v_and_b32_e32 v26, 64, v0
	s_and_b64 s[0:1], s[0:1], exec
	v_cmp_eq_u32_e32 vcc, 0, v26
	v_mov_b32_e32 v26, s69
	v_mov_b32_e32 v27, s67
	v_cndmask_b32_e32 v27, v26, v27, vcc
	v_mov_b32_e32 v26, s68
	v_mov_b32_e32 v28, s66
	s_movk_i32 s0, 0x100
	v_cndmask_b32_e32 v26, v26, v28, vcc
	v_cmp_gt_u32_e64 s[2:3], s0, v0
	v_mov_b32_e32 v28, 0x880
	v_mov_b32_e32 v46, 0x800
	v_lshrrev_b32_e32 v170, 1, v0
	v_and_b32_e32 v1, 63, v0
	v_writelane_b32 v250, s2, 21
	s_cselect_b32 s72, 17, 15
	s_add_u32 s88, s96, 0x2000000
	v_cndmask_b32_e64 v28, v28, v46, s[2:3]
	v_and_b32_e32 v46, 64, v170
	v_or3_b32 v28, v28, v46, v1
	v_lshlrev_b32_e32 v28, 2, v28
	v_lshl_add_u64 v[26:27], v[26:27], 0, v[28:29]
	global_load_dword v26, v[26:27], off
	s_addc_u32 s89, s97, 0
	s_add_i32 s0, 0, 0x24000
	s_lshl_b32 s55, s50, 4
	s_cmpk_gt_u32 s51, 0xff
	s_cselect_b64 s[4:5], -1, 0
	s_cmpk_lt_u32 s51, 0x100
	s_cselect_b64 vcc, -1, 0
	v_writelane_b32 v250, s3, 22
	s_and_b64 s[2:3], vcc, exec
	s_cselect_b32 s3, s45, s47
	s_cselect_b32 s2, s44, s46
	v_and_b32_e32 v110, 48, v0
	v_mov_b32_e32 v111, v29
	v_lshl_add_u32 v27, v0, 2, s0
	v_lshl_add_u64 v[112:113], s[2:3], 0, v[110:111]
	s_movk_i32 s2, 0x340
	v_cmp_gt_u32_e64 s[2:3], s2, v0
	v_bfe_u32 v171, v0, 4, 2
	s_mov_b32 s23, 0x1dc00
	v_writelane_b32 v250, s2, 23
	v_and_b32_e32 v166, 15, v0
	v_lshlrev_b32_e32 v173, 2, v171
	v_writelane_b32 v250, s3, 24
	s_mov_b32 s3, 0xd000
	s_cselect_b32 s2, 0, 0x4000
	s_cselect_b32 s22, s3, 0xf800
	v_or_b32_e32 v54, 16, v166
	v_or_b32_e32 v51, 32, v166
	v_bitop3_b32 v28, s50, v171, 3 bitop3:0x6c
	s_movk_i32 s73, 0xa0
	v_or_b32_e32 v49, 48, v1
	v_lshlrev_b32_e32 v48, 6, v28
	v_lshlrev_b32_e32 v28, 2, v166
	v_mul_u32_u24_e32 v46, 0xa0, v49
	v_lshlrev_b32_e32 v188, 2, v1
	v_and_b32_e32 v72, 4, v173
	v_lshrrev_b32_e32 v111, 3, v0
	v_or_b32_e32 v184, s55, v166
	v_mul_lo_u32 v185, v184, s73
	v_lshlrev_b32_e32 v172, 3, v171
	v_lshlrev_b32_e32 v61, 1, v166
	v_lshl_add_u32 v63, v166, 6, 0
	s_mov_b32 s1, 0
	v_and_or_b32 v176, s55, 48, v166
	v_or_b32_e32 v177, 0x200, v0
	v_or_b32_e32 v178, 0x400, v0
	v_or_b32_e32 v179, 0x600, v0
	v_mul_u32_u24_e32 v167, 0xa0, v166
	v_add_u32_e32 v205, 0x24800, v175
	v_lshrrev_b32_e32 v187, 6, v0
	v_add_u32_e32 v215, v63, v110
	v_mov_b32_e32 v220, 0x90
	v_mov_b32_e32 v138, 0
	s_waitcnt vmcnt(0)
	ds_write_b32 v27, v26
	v_and_b32_e32 v27, 7, v0
	v_lshl_add_u32 v180, v27, 5, s0
	s_mov_b32 s0, 0x8000
	s_cselect_b32 s0, s0, 0xa800
	s_add_i32 s0, s0, 0
	v_add_u32_e32 v181, s0, v110
	s_add_i32 s0, s2, 0
	v_lshl_add_u32 v47, v171, 10, s0
	s_lshl_b32 s0, s50, 8
	s_lshl_b32 s92, s50, 1
	s_add_i32 s0, s0, 0
	s_cmp_lt_u32 s51, 64
	s_cselect_b64 s[8:9], -1, 0
	s_cmpk_gt_u32 s51, 0x7f
	s_cselect_b64 s[10:11], -1, 0
	s_cmpk_gt_u32 s51, 0xbf
	s_cselect_b64 s[12:13], -1, 0
	s_cmpk_gt_u32 s51, 0x13f
	s_cselect_b64 s[14:15], -1, 0
	s_cmpk_gt_u32 s51, 0x17f
	s_cselect_b64 s[16:17], -1, 0
	s_cmpk_gt_u32 s51, 0x1bf
	s_cselect_b64 s[18:19], -1, 0
	s_cmpk_gt_u32 s51, 0x1ff
	v_writelane_b32 v250, s0, 25
	s_cselect_b64 s[20:21], -1, 0
	s_lshr_b32 s0, s51, 7
	s_cmp_eq_u32 s0, 2
	s_cselect_b64 s[2:3], -1, 0
	s_and_b64 s[6:7], s[2:3], exec
	s_cselect_b32 s6, s23, 0x20400
	s_cmp_lg_u32 s0, 1
	s_cselect_b32 s23, s6, 0x4000
	s_cmpk_lt_u32 s51, 0x80
	s_cselect_b64 s[24:25], -1, 0
	s_and_b64 s[6:7], s[24:25], exec
	s_cselect_b32 s6, 0, s23
	v_writelane_b32 v250, s24, 26
	s_or_b64 s[2:3], s[24:25], s[2:3]
	s_mov_b32 s7, 0x14800
	s_and_b64 s[2:3], s[2:3], exec
	s_cselect_b32 s7, s7, 0x12000
	s_bfe_u32 s54, s51, 0x10006
	s_bitcmp1_b32 s51, 6
	s_cselect_b64 s[2:3], -1, 0
	s_add_i32 s22, s22, 0
	v_writelane_b32 v250, s25, 27
	v_mov_b32_e32 v53, s22
	v_cmp_lt_u32_e64 s[22:23], v173, v166
	v_cmp_le_u32_e64 s[24:25], v173, v166
	s_add_i32 s7, s7, 0
	v_cndmask_b32_e64 v56, 0, 1, s[22:23]
	v_cndmask_b32_e64 v57, 0, 1, s[24:25]
	v_cndmask_b32_e32 v56, v57, v56, vcc
	v_and_b32_e32 v56, 1, v56
	v_cmp_eq_u32_e64 s[22:23], 1, v56
	v_or_b32_e32 v56, 17, v173
	v_cmp_lt_u32_e64 s[24:25], v56, v54
	v_cmp_le_u32_e64 s[26:27], v56, v54
	s_add_i32 s6, s6, 0
	v_cndmask_b32_e64 v56, 0, 1, s[24:25]
	v_cndmask_b32_e64 v57, 0, 1, s[26:27]
	v_cndmask_b32_e32 v56, v57, v56, vcc
	v_and_b32_e32 v56, 1, v56
	v_mov_b32_e32 v52, s7
	v_mov_b32_e32 v55, s6
	v_cmp_eq_u32_e64 s[6:7], 1, v56
	v_or_b32_e32 v56, 18, v173
	v_cmp_lt_u32_e64 s[26:27], v56, v54
	v_cmp_le_u32_e64 s[28:29], v56, v54
	v_writelane_b32 v250, s6, 28
	v_cndmask_b32_e64 v56, 0, 1, s[26:27]
	v_cndmask_b32_e64 v57, 0, 1, s[28:29]
	v_cndmask_b32_e32 v56, v57, v56, vcc
	v_and_b32_e32 v56, 1, v56
	v_writelane_b32 v250, s7, 29
	v_cmp_eq_u32_e64 s[6:7], 1, v56
	v_or_b32_e32 v56, 19, v173
	v_cmp_lt_u32_e64 s[28:29], v56, v54
	v_cmp_le_u32_e64 s[30:31], v56, v54
	v_writelane_b32 v250, s6, 30
	v_cndmask_b32_e64 v54, 0, 1, s[28:29]
	v_cndmask_b32_e64 v56, 0, 1, s[30:31]
	v_cndmask_b32_e32 v54, v56, v54, vcc
	v_and_b32_e32 v54, 1, v54
	v_writelane_b32 v250, s7, 31
	v_cmp_eq_u32_e64 s[6:7], 1, v54
	v_or_b32_e32 v54, 33, v173
	v_cmp_lt_u32_e64 s[30:31], v54, v51
	v_cmp_le_u32_e64 s[34:35], v54, v51
	v_writelane_b32 v250, s6, 32
	v_cndmask_b32_e64 v54, 0, 1, s[30:31]
	v_cndmask_b32_e64 v57, 0, 1, s[34:35]
	v_cndmask_b32_e32 v54, v57, v54, vcc
	v_and_b32_e32 v54, 1, v54
	v_writelane_b32 v250, s7, 33
	v_cmp_eq_u32_e64 s[6:7], 1, v54
	v_or_b32_e32 v54, 34, v173
	v_cmp_lt_u32_e64 s[34:35], v54, v51
	v_cmp_le_u32_e64 s[36:37], v54, v51
	v_writelane_b32 v250, s6, 34
	v_cndmask_b32_e64 v54, 0, 1, s[34:35]
	v_cndmask_b32_e64 v57, 0, 1, s[36:37]
	v_cndmask_b32_e32 v54, v57, v54, vcc
	v_and_b32_e32 v54, 1, v54
	v_writelane_b32 v250, s7, 35
	v_cmp_eq_u32_e64 s[6:7], 1, v54
	v_or_b32_e32 v54, 35, v173
	v_cmp_lt_u32_e64 s[36:37], v54, v51
	v_cmp_le_u32_e64 s[38:39], v54, v51
	v_writelane_b32 v250, s6, 36
	v_cndmask_b32_e64 v51, 0, 1, s[36:37]
	v_cndmask_b32_e64 v54, 0, 1, s[38:39]
	v_cndmask_b32_e32 v51, v54, v51, vcc
	v_and_b32_e32 v51, 1, v51
	v_add3_u32 v182, v47, v48, v28
	v_mad_u32_u24 v47, v166, s73, v52
	v_mad_u32_u24 v48, v166, s73, v53
	v_writelane_b32 v250, s7, 37
	v_cmp_eq_u32_e64 s[6:7], 1, v51
	v_mad_u32_u24 v51, v49, s73, v53
	v_mad_u32_u24 v53, v49, s73, v52
	v_cndmask_b32_e64 v52, 0, 1, vcc
	v_writelane_b32 v250, s6, 38
	v_or_b32_e32 v52, v173, v52
	v_mad_u32_u24 v183, v166, s73, v55
	v_writelane_b32 v250, s7, 39
	v_cmp_gt_u32_e64 s[6:7], v166, v52
	v_or_b32_e32 v52, 2, v173
	v_cmp_lt_u32_e64 s[40:41], v52, v166
	v_cmp_le_u32_e64 s[42:43], v52, v166
	v_writelane_b32 v250, s6, 40
	v_cndmask_b32_e64 v52, 0, 1, s[40:41]
	v_cndmask_b32_e64 v54, 0, 1, s[42:43]
	v_cndmask_b32_e32 v52, v54, v52, vcc
	v_and_b32_e32 v52, 1, v52
	v_writelane_b32 v250, s7, 41
	v_cmp_eq_u32_e64 s[6:7], 1, v52
	v_or_b32_e32 v52, 3, v173
	v_cmp_lt_u32_e64 s[42:43], v52, v166
	v_cmp_le_u32_e64 s[44:45], v52, v166
	v_writelane_b32 v250, s6, 42
	v_cndmask_b32_e64 v52, 0, 1, s[42:43]
	v_cndmask_b32_e64 v54, 0, 1, s[44:45]
	v_cndmask_b32_e32 v52, v54, v52, vcc
	v_and_b32_e32 v52, 1, v52
	v_writelane_b32 v250, s7, 43
	v_cmp_eq_u32_e64 s[6:7], 1, v52
	v_or_b32_e32 v52, 48, v173
	v_cmp_lt_u32_e64 s[44:45], v52, v49
	v_cmp_le_u32_e64 s[46:47], v52, v49
	v_mad_u32_u24 v189, v49, s73, v55
	v_cndmask_b32_e64 v54, 0, 1, s[44:45]
	v_cndmask_b32_e64 v55, 0, 1, s[46:47]
	v_cndmask_b32_e32 v54, v55, v54, vcc
	v_writelane_b32 v250, s6, 44
	v_and_b32_e32 v54, 1, v54
	s_mov_b32 s25, s50
	v_writelane_b32 v250, s7, 45
	v_cmp_eq_u32_e64 s[6:7], 1, v54
	v_or_b32_e32 v54, 49, v173
	v_cmp_lt_u32_e64 s[46:47], v54, v49
	v_cmp_le_u32_e64 s[48:49], v54, v49
	v_writelane_b32 v250, s6, 46
	v_cndmask_b32_e64 v54, 0, 1, s[46:47]
	v_cndmask_b32_e64 v55, 0, 1, s[48:49]
	v_cndmask_b32_e32 v54, v55, v54, vcc
	v_and_b32_e32 v54, 1, v54
	v_writelane_b32 v250, s7, 47
	v_cmp_eq_u32_e64 s[6:7], 1, v54
	v_or_b32_e32 v54, 50, v173
	v_cmp_lt_u32_e64 s[48:49], v54, v49
	s_mov_b32 s24, s51
	v_cmp_le_u32_e64 s[50:51], v54, v49
	v_cndmask_b32_e64 v54, 0, 1, s[48:49]
	v_writelane_b32 v250, s6, 48
	v_cndmask_b32_e64 v55, 0, 1, s[50:51]
	v_cndmask_b32_e32 v54, v55, v54, vcc
	v_and_b32_e32 v54, 1, v54
	v_writelane_b32 v250, s7, 49
	v_cmp_eq_u32_e64 s[6:7], 1, v54
	v_or_b32_e32 v54, 51, v173
	v_cmp_lt_u32_e64 s[50:51], v54, v49
	v_cmp_le_u32_e64 s[52:53], v54, v49
	v_writelane_b32 v250, s6, 50
	v_cndmask_b32_e64 v49, 0, 1, s[50:51]
	v_cndmask_b32_e64 v54, 0, 1, s[52:53]
	v_cndmask_b32_e32 v49, v54, v49, vcc
	v_and_b32_e32 v49, 1, v49
	v_writelane_b32 v250, s7, 51
	v_cmp_eq_u32_e64 s[6:7], 1, v49
	v_lshlrev_b32_e32 v49, 1, v52
	v_add_u32_e32 v57, 0, v28
	v_writelane_b32 v250, s6, 52
	v_lshl_or_b32 v52, s54, 5, v166
	v_mul_u32_u24_e32 v58, 0x90, v52
	v_writelane_b32 v250, s7, 53
	s_movk_i32 s7, 0x9c
	v_or_b32_e32 v52, 16, v52
	v_mad_u32_u24 v60, v166, s7, v57
	s_movk_i32 s7, 0x480
	v_mul_u32_u24_e32 v59, 0x90, v52
	v_mad_u32_u24 v52, v171, s7, 0
	s_and_b32 s7, s24, 0xffffffc0
	s_lshl_b32 s26, s0, 4
	v_add3_u32 v191, v52, s7, v28
	v_lshlrev_b32_e32 v28, 9, v171
	v_or_b32_e32 v168, s26, v166
	s_movk_i32 s6, 0x90
	v_writelane_b32 v250, s24, 54
	v_sub_u32_e32 v28, v52, v28
	v_lshl_add_u32 v62, s25, 5, v28
	v_writelane_b32 v250, s55, 55
	v_mul_lo_u32 v28, v168, s6
	s_add_i32 s6, 0, 0x20400
	s_add_i32 s93, 0, 0x1b800
	s_add_i32 s40, 0, 0x12000
	s_and_b32 s7, s92, 2
	s_add_i32 s24, 0, 0x1dc00
	v_add_u32_e32 v193, s6, v110
	s_add_i32 s6, s26, 64
	s_add_i32 s41, 0, 0x19400
	s_add_i32 s42, 0, 0x17000
	v_writelane_b32 v250, s25, 56
	s_bitcmp1_b32 s25, 0
	v_writelane_b32 v250, s26, 57
	v_or_b32_e32 v73, s26, v173
	s_movk_i32 s43, 0x120
	v_add_u32_e32 v66, s93, v28
	v_or_b32_e32 v52, s6, v166
	v_add_u32_e32 v68, s42, v28
	v_add_u32_e32 v69, s41, v28
	v_lshl_or_b32 v70, s7, 4, v166
	s_cselect_b64 s[62:63], -1, 0
	s_lshl_b32 s6, s7, 10
	v_lshl_or_b32 v169, s0, 8, v188
	s_or_b32 s0, s7, 1
	v_mul_lo_u32 v28, v73, s43
	v_writelane_b32 v250, s54, 58
	s_lshl_b32 s7, s54, 7
	v_add_u32_e32 v192, s24, v110
	s_add_i32 s24, 0, 0x22c00
	v_lshl_or_b32 v71, s0, 4, v166
	s_lshl_b32 s0, s0, 10
	v_add3_u32 v202, v57, v28, s7
	v_lshlrev_b32_e32 v28, 1, v73
	s_mov_b32 s7, 0x1ffffff0
	v_readlane_b32 s26, v250, 19
	v_and_or_b32 v57, v28, s7, v166
	v_readlane_b32 s27, v250, 20
	s_add_u32 s38, s66, 0x1000
	v_add_u32_e32 v203, 0, v28
	v_lshl_add_u64 v[118:119], s[26:27], 0, v[28:29]
	v_lshlrev_b32_e32 v28, 3, v57
	s_addc_u32 s39, s67, 0
	v_add_u32_e32 v114, s6, v169
	v_add_u32_e32 v57, s6, v28
	s_add_u32 s6, s68, 0x800
	s_addc_u32 s7, s69, 0
	v_or_b32_e32 v120, v57, v72
	v_or_b32_e32 v57, 1, v73
	v_cmp_eq_u32_e64 s[52:53], v73, v70
	v_add_u32_e32 v28, s0, v28
	v_writelane_b32 v250, s6, 59
	v_cmp_eq_u32_e32 vcc, v57, v70
	v_cndmask_b32_e64 v122, 0, 1.0, s[52:53]
	v_or_b32_e32 v124, v28, v72
	v_cmp_eq_u32_e64 s[52:53], v73, v71
	v_or_b32_e32 v28, 3, v73
	v_writelane_b32 v250, s7, 60
	s_add_u32 s6, s66, 0x800
	v_cndmask_b32_e64 v123, 0, 1.0, vcc
	v_cmp_eq_u32_e32 vcc, v57, v71
	v_cndmask_b32_e64 v126, 0, 1.0, s[52:53]
	v_or_b32_e32 v57, 2, v73
	v_cmp_eq_u32_e64 s[52:53], v28, v70
	s_addc_u32 s7, s67, 0
	v_mad_u32_u24 v26, v111, s73, 0
	v_lshlrev_b32_e32 v27, 4, v27
	v_mul_lo_u32 v186, v168, s73
	v_mul_lo_u32 v52, v52, s73
	v_cndmask_b32_e64 v127, 0, 1.0, vcc
	v_cmp_eq_u32_e32 vcc, v57, v70
	v_cndmask_b32_e64 v129, 0, 1.0, s[52:53]
	v_cmp_eq_u32_e64 s[52:53], v28, v71
	v_writelane_b32 v250, s6, 61
	v_lshlrev_b32_e32 v28, 5, v0
	v_add_u32_e32 v50, 0xa00, v183
	v_add_u32_e32 v56, 0x1400, v183
	v_add_u32_e32 v55, 0, v186
	v_add_u32_e32 v190, s93, v110
	v_add_u32_e32 v64, s40, v185
	v_add_u32_e32 v65, s40, v186
	v_add_u32_e32 v67, s40, v52
	v_lshlrev_b32_e32 v52, 6, v70
	v_lshlrev_b32_e32 v54, 6, v71
	v_add_u32_e32 v116, s0, v169
	v_cndmask_b32_e64 v128, 0, 1.0, vcc
	v_cmp_eq_u32_e32 vcc, v57, v71
	v_writelane_b32 v250, s7, 62
	s_add_u32 s6, s68, 0x1000
	v_and_b32_e32 v28, 0x3800, v28
	v_add_u32_e32 v206, v26, v27
	v_add_u32_e32 v207, v181, v46
	v_mbcnt_lo_u32_b32 v26, -1, 0
	v_mov_b32_e32 v46, 0
	v_add_u32_e32 v194, s41, v110
	v_add_u32_e32 v195, s40, v110
	v_mul_u32_u24_e32 v196, 0xa0, v70
	v_mul_u32_u24_e32 v197, 0x90, v70
	v_lshl_add_u32 v198, v70, 2, s24
	v_ashrrev_i32_e32 v115, 31, v114
	v_mul_u32_u24_e32 v199, 0xa0, v71
	v_mul_u32_u24_e32 v200, 0x90, v71
	v_lshl_add_u32 v201, v71, 2, s24
	v_ashrrev_i32_e32 v117, 31, v116
	v_lshl_add_u32 v204, v73, 2, s24
	v_ashrrev_i32_e32 v121, 31, v120
	v_ashrrev_i32_e32 v125, 31, v124
	v_cndmask_b32_e64 v131, 0, 1.0, s[52:53]
	v_cndmask_b32_e64 v130, 0, 1.0, vcc
	s_addc_u32 s7, s69, 0
	v_lshl_add_u64 v[132:133], s[70:71], 0, v[28:29]
	s_mov_b32 s34, -1
	s_movk_i32 s71, 0x630
	s_mov_b32 s44, 0x3e0f83e1
	s_movk_i32 s45, 0xfdf0
	s_movk_i32 s46, 0x2940
	s_mov_b32 s47, 0x5040100
	s_mov_b32 s70, 0xbf60033a
	v_mbcnt_hi_u32_b32 v208, -1, v26
	s_add_i32 s48, 0, 0x12280
	s_movk_i32 s49, 0x2600
	v_add_u32_e32 v209, v50, v172
	v_add_u32_e32 v210, v51, v110
	v_add_u32_e32 v211, v53, v110
	v_add_u32_e32 v212, v189, v49
	v_add_u32_e32 v213, v60, v172
	v_add_u32_e32 v214, v62, v61
	v_add_u32_e32 v216, v64, v172
	v_add_u32_e32 v217, v65, v110
	v_lshlrev_b32_e32 v134, 1, v52
	v_add_u32_e32 v218, v68, v110
	v_add_u32_e32 v219, v69, v110
	v_lshlrev_b32_e32 v136, 1, v54
	v_add_u32_e32 v221, v47, v110
	v_add_u32_e32 v222, v48, v110
	v_add_u32_e32 v223, v56, v172
	v_mov_b32_e32 v139, v46
	v_add_u32_e32 v224, v55, v110
	v_add_u32_e32 v225, v190, v58
	v_add_u32_e32 v226, v190, v59
	v_add_u32_e32 v227, v66, v110
	v_add_u32_e32 v228, v67, v110
	s_mov_b32 s51, 0
	v_lshrrev_b32_e32 v26, 3, v0
	v_and_b32_e32 v27, 7, v0
	v_mul_u32_u24_e32 v26, 0x2600, v26
	v_lshl_add_u32 v251, v27, 4, v26
	v_mov_b32_e32 v26, v0
	v_lshrrev_b32_e32 v27, 4, v26
	v_mul_u32_u24_e32 v27, 0x7c2, v27
	v_lshrrev_b32_e32 v27, 16, v27
	v_mul_u32_u24_e32 v28, 0x210, v27
	v_sub_u32_e32 v26, v26, v28
	v_lshrrev_b32_e32 v28, 3, v26
	v_and_b32_e32 v26, 7, v26
	v_mul_u32_u24_e32 v28, 0x2600, v28
	v_lshl_add_u32 v28, v27, 10, v28
	v_lshl_add_u32 v252, v26, 4, v28
	v_add_u32_e32 v26, 0x200, v0
	v_lshrrev_b32_e32 v27, 4, v26
	v_mul_u32_u24_e32 v27, 0x7c2, v27
	v_lshrrev_b32_e32 v27, 16, v27
	v_mul_u32_u24_e32 v28, 0x210, v27
	v_sub_u32_e32 v26, v26, v28
	v_lshrrev_b32_e32 v28, 3, v26
	v_and_b32_e32 v26, 7, v26
	v_mul_u32_u24_e32 v28, 0x2600, v28
	v_lshl_add_u32 v28, v27, 10, v28
	v_lshl_add_u32 v253, v26, 4, v28
	v_add_u32_e32 v26, 0x400, v0
	v_lshrrev_b32_e32 v27, 4, v26
	v_mul_u32_u24_e32 v27, 0x7c2, v27
	v_lshrrev_b32_e32 v27, 16, v27
	v_mul_u32_u24_e32 v28, 0x210, v27
	v_sub_u32_e32 v26, v26, v28
	v_lshrrev_b32_e32 v28, 3, v26
	v_and_b32_e32 v26, 7, v26
	v_mul_u32_u24_e32 v28, 0x2600, v28
	v_lshl_add_u32 v28, v27, 10, v28
	v_lshl_add_u32 v254, v26, 4, v28
	v_add_u32_e32 v26, 0x600, v0
	v_lshrrev_b32_e32 v27, 4, v26
	v_mul_u32_u24_e32 v27, 0x7c2, v27
	v_lshrrev_b32_e32 v27, 16, v27
	v_mul_u32_u24_e32 v28, 0x210, v27
	v_sub_u32_e32 v26, v26, v28
	v_lshrrev_b32_e32 v28, 3, v26
	v_and_b32_e32 v26, 7, v26
	v_mul_u32_u24_e32 v28, 0x2600, v28
	v_lshl_add_u32 v28, v27, 10, v28
	v_lshl_add_u32 v255, v26, 4, v28
	s_branch .LBB0_295

.Lhg_rel0:
	s_or_b64 exec, exec, s[38:39]
	s_waitcnt vmcnt(16)
	v_lshlrev_b32_e32 v76, 16, v10
	v_and_b32_e32 v77, 0xffff0000, v10
	v_lshlrev_b32_e32 v78, 16, v11
	v_and_b32_e32 v79, 0xffff0000, v11
	v_lshlrev_b32_e32 v80, 16, v12
	v_and_b32_e32 v81, 0xffff0000, v12
	v_lshlrev_b32_e32 v82, 16, v13
	v_and_b32_e32 v83, 0xffff0000, v13
	v_lshlrev_b32_e32 v84, 16, v14
	v_and_b32_e32 v85, 0xffff0000, v14
	v_lshlrev_b32_e32 v86, 16, v15
	v_and_b32_e32 v87, 0xffff0000, v15
	v_lshlrev_b32_e32 v88, 16, v16
	v_and_b32_e32 v89, 0xffff0000, v16
	v_lshlrev_b32_e32 v90, 16, v17
	v_and_b32_e32 v91, 0xffff0000, v17
	v_lshlrev_b32_e32 v92, 16, v18
	v_and_b32_e32 v93, 0xffff0000, v18
	v_lshlrev_b32_e32 v94, 16, v19
	v_and_b32_e32 v95, 0xffff0000, v19
	v_lshlrev_b32_e32 v96, 16, v20
	v_and_b32_e32 v97, 0xffff0000, v20
	v_lshlrev_b32_e32 v98, 16, v21
	v_and_b32_e32 v99, 0xffff0000, v21
	v_lshlrev_b32_e32 v100, 16, v22
	v_and_b32_e32 v101, 0xffff0000, v22
	v_lshlrev_b32_e32 v102, 16, v23
	v_and_b32_e32 v103, 0xffff0000, v23
	v_lshlrev_b32_e32 v104, 16, v24
	v_and_b32_e32 v105, 0xffff0000, v24
	v_lshlrev_b32_e32 v106, 16, v25
	v_and_b32_e32 v107, 0xffff0000, v25
	v_pk_add_f32 v[140:141], v[76:77], 1.0 op_sel_hi:[1,0] neg_lo:[1,0] neg_hi:[1,0]
	v_pk_add_f32 v[142:143], v[78:79], 1.0 op_sel_hi:[1,0] neg_lo:[1,0] neg_hi:[1,0]
	v_pk_add_f32 v[226:227], v[80:81], 1.0 op_sel_hi:[1,0] neg_lo:[1,0] neg_hi:[1,0]
	v_pk_add_f32 v[228:229], v[82:83], 1.0 op_sel_hi:[1,0] neg_lo:[1,0] neg_hi:[1,0]
	v_pk_mul_f32 v[144:145], v[140:141], v[226:227]
	v_pk_mul_f32 v[146:147], v[142:143], v[228:229]
	v_pk_add_f32 v[230:231], v[84:85], 1.0 op_sel_hi:[1,0] neg_lo:[1,0] neg_hi:[1,0]
	v_pk_add_f32 v[232:233], v[86:87], 1.0 op_sel_hi:[1,0] neg_lo:[1,0] neg_hi:[1,0]
	v_pk_mul_f32 v[148:149], v[144:145], v[230:231]
	v_pk_mul_f32 v[150:151], v[146:147], v[232:233]
	v_pk_add_f32 v[234:235], v[88:89], 1.0 op_sel_hi:[1,0] neg_lo:[1,0] neg_hi:[1,0]
	v_pk_add_f32 v[236:237], v[90:91], 1.0 op_sel_hi:[1,0] neg_lo:[1,0] neg_hi:[1,0]
	v_pk_mul_f32 v[152:153], v[148:149], v[234:235]
	v_pk_mul_f32 v[154:155], v[150:151], v[236:237]
	v_pk_add_f32 v[238:239], v[92:93], 1.0 op_sel_hi:[1,0] neg_lo:[1,0] neg_hi:[1,0]
	v_pk_add_f32 v[240:241], v[94:95], 1.0 op_sel_hi:[1,0] neg_lo:[1,0] neg_hi:[1,0]
	v_pk_mul_f32 v[156:157], v[152:153], v[238:239]
	v_pk_mul_f32 v[158:159], v[154:155], v[240:241]
	v_pk_add_f32 v[242:243], v[96:97], 1.0 op_sel_hi:[1,0] neg_lo:[1,0] neg_hi:[1,0]
	v_pk_add_f32 v[244:245], v[98:99], 1.0 op_sel_hi:[1,0] neg_lo:[1,0] neg_hi:[1,0]
	v_pk_mul_f32 v[160:161], v[156:157], v[242:243]
	v_pk_mul_f32 v[162:163], v[158:159], v[244:245]
	v_pk_add_f32 v[246:247], v[100:101], 1.0 op_sel_hi:[1,0] neg_lo:[1,0] neg_hi:[1,0]
	v_pk_add_f32 v[248:249], v[102:103], 1.0 op_sel_hi:[1,0] neg_lo:[1,0] neg_hi:[1,0]
	v_pk_mul_f32 v[164:165], v[160:161], v[246:247]
	v_pk_mul_f32 v[166:167], v[162:163], v[248:249]
	v_pk_add_f32 v[74:75], v[104:105], 1.0 op_sel_hi:[1,0] neg_lo:[1,0] neg_hi:[1,0]
	v_pk_add_f32 v[172:173], v[106:107], 1.0 op_sel_hi:[1,0] neg_lo:[1,0] neg_hi:[1,0]
	v_pk_mul_f32 v[168:169], v[164:165], v[74:75]
	v_pk_mul_f32 v[170:171], v[166:167], v[172:173]
	v_lshlrev_b32_e32 v108, 16, v26
	v_and_b32_e32 v109, 0xffff0000, v26
	v_lshlrev_b32_e32 v110, 16, v27
	v_and_b32_e32 v111, 0xffff0000, v27
	v_lshlrev_b32_e32 v112, 16, v28
	v_and_b32_e32 v113, 0xffff0000, v28
	v_lshlrev_b32_e32 v114, 16, v29
	v_and_b32_e32 v115, 0xffff0000, v29
	v_lshlrev_b32_e32 v116, 16, v30
	v_and_b32_e32 v117, 0xffff0000, v30
	v_lshlrev_b32_e32 v118, 16, v31
	v_and_b32_e32 v119, 0xffff0000, v31
	v_lshlrev_b32_e32 v120, 16, v32
	v_and_b32_e32 v121, 0xffff0000, v32
	v_lshlrev_b32_e32 v122, 16, v33
	v_and_b32_e32 v123, 0xffff0000, v33
	v_lshlrev_b32_e32 v124, 16, v34
	v_and_b32_e32 v125, 0xffff0000, v34
	v_lshlrev_b32_e32 v126, 16, v35
	v_and_b32_e32 v127, 0xffff0000, v35
	v_lshlrev_b32_e32 v128, 16, v36
	v_and_b32_e32 v129, 0xffff0000, v36
	v_lshlrev_b32_e32 v130, 16, v37
	v_and_b32_e32 v131, 0xffff0000, v37
	v_lshlrev_b32_e32 v132, 16, v38
	v_and_b32_e32 v133, 0xffff0000, v38
	v_lshlrev_b32_e32 v134, 16, v39
	v_and_b32_e32 v135, 0xffff0000, v39
	v_lshlrev_b32_e32 v136, 16, v40
	v_and_b32_e32 v137, 0xffff0000, v40
	v_lshlrev_b32_e32 v138, 16, v41
	v_and_b32_e32 v139, 0xffff0000, v41
	global_load_dwordx2 v[10:11], v3, s[8:9]
	global_load_dwordx2 v[26:27], v2, s[8:9]
	s_add_u32 s8, s8, s10
	s_addc_u32 s9, s9, s11
	global_load_dwordx2 v[12:13], v3, s[8:9]
	global_load_dwordx2 v[28:29], v2, s[8:9]
	s_add_u32 s8, s8, s10
	s_addc_u32 s9, s9, s11
	global_load_dwordx2 v[14:15], v3, s[8:9]
	global_load_dwordx2 v[30:31], v2, s[8:9]
	s_add_u32 s8, s8, s10
	s_addc_u32 s9, s9, s11
	global_load_dwordx2 v[16:17], v3, s[8:9]
	global_load_dwordx2 v[32:33], v2, s[8:9]
	s_add_u32 s8, s8, s10
	s_addc_u32 s9, s9, s11
	global_load_dwordx2 v[18:19], v3, s[8:9]
	global_load_dwordx2 v[34:35], v2, s[8:9]
	s_add_u32 s8, s8, s10
	s_addc_u32 s9, s9, s11
	global_load_dwordx2 v[20:21], v3, s[8:9]
	global_load_dwordx2 v[36:37], v2, s[8:9]
	s_add_u32 s8, s8, s10
	s_addc_u32 s9, s9, s11
	global_load_dwordx2 v[22:23], v3, s[8:9]
	global_load_dwordx2 v[38:39], v2, s[8:9]
	s_add_u32 s8, s8, s10
	s_addc_u32 s9, s9, s11
	global_load_dwordx2 v[24:25], v3, s[8:9]
	global_load_dwordx2 v[40:41], v2, s[8:9]
	s_add_u32 s8, s8, s10
	s_addc_u32 s9, s9, s11
	s_cmp_lt_u32 s16, 63
	s_cselect_b32 s34, s12, s14
	s_cselect_b32 s35, s13, s15
	s_add_u32 s8, s8, s34
	s_addc_u32 s9, s9, s35
	s_add_i32 s16, s16, 1
	v_mov_b32_e32 v192, 1.0
	v_mov_b32_e32 v193, 1.0
	v_mov_b32_e32 v194, 1.0
	v_mov_b32_e32 v195, 1.0
	v_mov_b32_dpp v192, v168 row_shr:8 row_mask:0xf bank_mask:0xc
	v_mov_b32_dpp v193, v169 row_shr:8 row_mask:0xf bank_mask:0xc
	v_mov_b32_dpp v194, v170 row_shr:8 row_mask:0xf bank_mask:0xc
	v_mov_b32_dpp v195, v171 row_shr:8 row_mask:0xf bank_mask:0xc
	v_mul_f32_dpp v196, v168, v168 row_ror:8 row_mask:0xf bank_mask:0xf
	v_mul_f32_dpp v197, v169, v169 row_ror:8 row_mask:0xf bank_mask:0xf
	v_mul_f32_dpp v198, v170, v170 row_ror:8 row_mask:0xf bank_mask:0xf
	v_mul_f32_dpp v199, v171, v171 row_ror:8 row_mask:0xf bank_mask:0xf
	v_mov_b32_e32 v200, v196
	v_mov_b32_e32 v201, v197
	v_mov_b32_e32 v202, v198
	v_mov_b32_e32 v203, v199
	v_permlane16_swap_b32_e32 v196, v200
	v_permlane16_swap_b32_e32 v197, v201
	v_permlane16_swap_b32_e32 v198, v202
	v_permlane16_swap_b32_e32 v199, v203
	v_pk_mul_f32 v[204:205], v[196:197], v[200:201]
	v_pk_mul_f32 v[206:207], v[198:199], v[202:203]
	v_mov_b32_e32 v208, v204
	v_mov_b32_e32 v209, v205
	v_mov_b32_e32 v210, v206
	v_mov_b32_e32 v211, v207
	v_mov_b32_e32 v212, 1.0
	v_mov_b32_e32 v213, 1.0
	v_mov_b32_e32 v214, 1.0
	v_mov_b32_e32 v215, 1.0
	v_permlane32_swap_b32_e32 v204, v208
	v_permlane32_swap_b32_e32 v205, v209
	v_permlane32_swap_b32_e32 v206, v210
	v_permlane32_swap_b32_e32 v207, v211
	s_mov_b64 s[34:35], exec
	s_mov_b64 exec, 0xffff0000
	v_mov_b32_e32 v212, v196
	v_mov_b32_e32 v213, v197
	v_mov_b32_e32 v214, v198
	v_mov_b32_e32 v215, v199
	s_mov_b32 exec_lo, 0
	s_mov_b32 exec_hi, -1
	v_mov_b32_e32 v212, v204
	v_mov_b32_e32 v213, v205
	v_mov_b32_e32 v214, v206
	v_mov_b32_e32 v215, v207
	s_mov_b32 exec_hi, 0xffff0000
	v_pk_mul_f32 v[212:213], v[212:213], v[196:197]
	v_pk_mul_f32 v[214:215], v[214:215], v[198:199]
	s_mov_b64 exec, s[34:35]
	v_pk_mul_f32 v[176:177], v[212:213], v[192:193]
	v_pk_mul_f32 v[178:179], v[214:215], v[194:195]
	v_pk_mul_f32 v[188:189], v[176:177], v[168:169]
	v_pk_mul_f32 v[190:191], v[178:179], v[170:171]
	s_mov_b64 s[34:35], exec
	s_mov_b64 exec, s[30:31]
	ds_write_b128 v8, v[188:191]
	s_mov_b64 exec, s[34:35]
	v_max_f32_e32 v180, 0xda24260, v188
	v_max_f32_e32 v181, 0xda24260, v189
	v_max_f32_e32 v182, 0xda24260, v190
	v_max_f32_e32 v183, 0xda24260, v191
	v_rcp_f32_e32 v180, v180
	v_rcp_f32_e32 v181, v181
	v_rcp_f32_e32 v182, v182
	v_rcp_f32_e32 v183, v183
	v_pk_mul_f32 v[192:193], v[136:137], v[188:189]
	v_pk_mul_f32 v[194:195], v[138:139], v[190:191]
	v_pk_mul_f32 v[196:197], v[104:105], v[180:181]
	v_pk_mul_f32 v[198:199], v[106:107], v[182:183]
	v_cvt_pk_bf16_f32 v204, v192, v193
	v_cvt_pk_bf16_f32 v205, v194, v195
	ds_write_b64 v4, v[204:205] offset:2016
	v_cvt_pk_bf16_f32 v206, v196, v197
	v_cvt_pk_bf16_f32 v207, v198, v199
	ds_write_b64 v4, v[206:207] offset:38880
	v_pk_mul_f32 v[180:181], v[180:181], v[74:75]
	v_pk_mul_f32 v[182:183], v[182:183], v[172:173]
	v_pk_mul_f32 v[188:189], v[176:177], v[164:165]
	v_pk_mul_f32 v[190:191], v[178:179], v[166:167]
	v_pk_mul_f32 v[192:193], v[132:133], v[188:189]
	v_pk_mul_f32 v[194:195], v[134:135], v[190:191]
	v_pk_mul_f32 v[200:201], v[100:101], v[180:181]
	v_pk_mul_f32 v[202:203], v[102:103], v[182:183]
	v_cvt_pk_bf16_f32 v204, v192, v193
	v_cvt_pk_bf16_f32 v205, v194, v195
	ds_write_b64 v4, v[204:205] offset:1728
	v_cvt_pk_bf16_f32 v206, v200, v201
	v_cvt_pk_bf16_f32 v207, v202, v203
	ds_write_b64 v4, v[206:207] offset:38592
	v_pk_mul_f32 v[180:181], v[180:181], v[246:247]
	v_pk_mul_f32 v[182:183], v[182:183], v[248:249]
	v_pk_mul_f32 v[188:189], v[176:177], v[160:161]
	v_pk_mul_f32 v[190:191], v[178:179], v[162:163]
	v_pk_mul_f32 v[192:193], v[128:129], v[188:189]
	v_pk_mul_f32 v[194:195], v[130:131], v[190:191]
	v_pk_mul_f32 v[196:197], v[96:97], v[180:181]
	v_pk_mul_f32 v[198:199], v[98:99], v[182:183]
	v_cvt_pk_bf16_f32 v204, v192, v193
	v_cvt_pk_bf16_f32 v205, v194, v195
	ds_write_b64 v4, v[204:205] offset:1440
	v_cvt_pk_bf16_f32 v206, v196, v197
	v_cvt_pk_bf16_f32 v207, v198, v199
	ds_write_b64 v4, v[206:207] offset:38304
	v_pk_mul_f32 v[180:181], v[180:181], v[242:243]
	v_pk_mul_f32 v[182:183], v[182:183], v[244:245]
	v_pk_mul_f32 v[188:189], v[176:177], v[156:157]
	v_pk_mul_f32 v[190:191], v[178:179], v[158:159]
	v_pk_mul_f32 v[192:193], v[124:125], v[188:189]
	v_pk_mul_f32 v[194:195], v[126:127], v[190:191]
	v_pk_mul_f32 v[200:201], v[92:93], v[180:181]
	v_pk_mul_f32 v[202:203], v[94:95], v[182:183]
	v_cvt_pk_bf16_f32 v204, v192, v193
	v_cvt_pk_bf16_f32 v205, v194, v195
	ds_write_b64 v4, v[204:205] offset:1152
	v_cvt_pk_bf16_f32 v206, v200, v201
	v_cvt_pk_bf16_f32 v207, v202, v203
	ds_write_b64 v4, v[206:207] offset:38016
	v_pk_mul_f32 v[180:181], v[180:181], v[238:239]
	v_pk_mul_f32 v[182:183], v[182:183], v[240:241]
	v_pk_mul_f32 v[188:189], v[176:177], v[152:153]
	v_pk_mul_f32 v[190:191], v[178:179], v[154:155]
	v_pk_mul_f32 v[192:193], v[120:121], v[188:189]
	v_pk_mul_f32 v[194:195], v[122:123], v[190:191]
	v_pk_mul_f32 v[196:197], v[88:89], v[180:181]
	v_pk_mul_f32 v[198:199], v[90:91], v[182:183]
	v_cvt_pk_bf16_f32 v204, v192, v193
	v_cvt_pk_bf16_f32 v205, v194, v195
	ds_write_b64 v4, v[204:205] offset:864
	v_cvt_pk_bf16_f32 v206, v196, v197
	v_cvt_pk_bf16_f32 v207, v198, v199
	ds_write_b64 v4, v[206:207] offset:37728
	v_pk_mul_f32 v[180:181], v[180:181], v[234:235]
	v_pk_mul_f32 v[182:183], v[182:183], v[236:237]
	v_pk_mul_f32 v[188:189], v[176:177], v[148:149]
	v_pk_mul_f32 v[190:191], v[178:179], v[150:151]
	v_pk_mul_f32 v[192:193], v[116:117], v[188:189]
	v_pk_mul_f32 v[194:195], v[118:119], v[190:191]
	v_pk_mul_f32 v[200:201], v[84:85], v[180:181]
	v_pk_mul_f32 v[202:203], v[86:87], v[182:183]
	v_cvt_pk_bf16_f32 v204, v192, v193
	v_cvt_pk_bf16_f32 v205, v194, v195
	ds_write_b64 v4, v[204:205] offset:576
	v_cvt_pk_bf16_f32 v206, v200, v201
	v_cvt_pk_bf16_f32 v207, v202, v203
	ds_write_b64 v4, v[206:207] offset:37440
	v_pk_mul_f32 v[180:181], v[180:181], v[230:231]
	v_pk_mul_f32 v[182:183], v[182:183], v[232:233]
	v_pk_mul_f32 v[188:189], v[176:177], v[144:145]
	v_pk_mul_f32 v[190:191], v[178:179], v[146:147]
	v_pk_mul_f32 v[192:193], v[112:113], v[188:189]
	v_pk_mul_f32 v[194:195], v[114:115], v[190:191]
	v_pk_mul_f32 v[196:197], v[80:81], v[180:181]
	v_pk_mul_f32 v[198:199], v[82:83], v[182:183]
	v_cvt_pk_bf16_f32 v204, v192, v193
	v_cvt_pk_bf16_f32 v205, v194, v195
	ds_write_b64 v4, v[204:205] offset:288
	v_cvt_pk_bf16_f32 v206, v196, v197
	v_cvt_pk_bf16_f32 v207, v198, v199
	ds_write_b64 v4, v[206:207] offset:37152
	v_pk_mul_f32 v[180:181], v[180:181], v[226:227]
	v_pk_mul_f32 v[182:183], v[182:183], v[228:229]
	v_pk_mul_f32 v[188:189], v[176:177], v[140:141]
	v_pk_mul_f32 v[190:191], v[178:179], v[142:143]
	v_pk_mul_f32 v[192:193], v[108:109], v[188:189]
	v_pk_mul_f32 v[194:195], v[110:111], v[190:191]
	v_pk_mul_f32 v[200:201], v[76:77], v[180:181]
	v_pk_mul_f32 v[202:203], v[78:79], v[182:183]
	v_cvt_pk_bf16_f32 v204, v192, v193
	v_cvt_pk_bf16_f32 v205, v194, v195
	ds_write_b64 v4, v[204:205]
	v_cvt_pk_bf16_f32 v206, v200, v201
	v_cvt_pk_bf16_f32 v207, v202, v203
	ds_write_b64 v4, v[206:207] offset:36864
	s_waitcnt vmcnt(16)
	v_lshlrev_b32_e32 v76, 16, v42
	v_and_b32_e32 v77, 0xffff0000, v42
	v_lshlrev_b32_e32 v78, 16, v43
	v_and_b32_e32 v79, 0xffff0000, v43
	v_lshlrev_b32_e32 v80, 16, v44
	v_and_b32_e32 v81, 0xffff0000, v44
	v_lshlrev_b32_e32 v82, 16, v45
	v_and_b32_e32 v83, 0xffff0000, v45
	v_lshlrev_b32_e32 v84, 16, v46
	v_and_b32_e32 v85, 0xffff0000, v46
	v_lshlrev_b32_e32 v86, 16, v47
	v_and_b32_e32 v87, 0xffff0000, v47
	v_lshlrev_b32_e32 v88, 16, v48
	v_and_b32_e32 v89, 0xffff0000, v48
	v_lshlrev_b32_e32 v90, 16, v49
	v_and_b32_e32 v91, 0xffff0000, v49
	v_lshlrev_b32_e32 v92, 16, v50
	v_and_b32_e32 v93, 0xffff0000, v50
	v_lshlrev_b32_e32 v94, 16, v51
	v_and_b32_e32 v95, 0xffff0000, v51
	v_lshlrev_b32_e32 v96, 16, v52
	v_and_b32_e32 v97, 0xffff0000, v52
	v_lshlrev_b32_e32 v98, 16, v53
	v_and_b32_e32 v99, 0xffff0000, v53
	v_lshlrev_b32_e32 v100, 16, v54
	v_and_b32_e32 v101, 0xffff0000, v54
	v_lshlrev_b32_e32 v102, 16, v55
	v_and_b32_e32 v103, 0xffff0000, v55
	v_lshlrev_b32_e32 v104, 16, v56
	v_and_b32_e32 v105, 0xffff0000, v56
	v_lshlrev_b32_e32 v106, 16, v57
	v_and_b32_e32 v107, 0xffff0000, v57
	v_pk_add_f32 v[140:141], v[76:77], 1.0 op_sel_hi:[1,0] neg_lo:[1,0] neg_hi:[1,0]
	v_pk_add_f32 v[142:143], v[78:79], 1.0 op_sel_hi:[1,0] neg_lo:[1,0] neg_hi:[1,0]
	v_pk_add_f32 v[226:227], v[80:81], 1.0 op_sel_hi:[1,0] neg_lo:[1,0] neg_hi:[1,0]
	v_pk_add_f32 v[228:229], v[82:83], 1.0 op_sel_hi:[1,0] neg_lo:[1,0] neg_hi:[1,0]
	v_pk_mul_f32 v[144:145], v[140:141], v[226:227]
	v_pk_mul_f32 v[146:147], v[142:143], v[228:229]
	v_pk_add_f32 v[230:231], v[84:85], 1.0 op_sel_hi:[1,0] neg_lo:[1,0] neg_hi:[1,0]
	v_pk_add_f32 v[232:233], v[86:87], 1.0 op_sel_hi:[1,0] neg_lo:[1,0] neg_hi:[1,0]
	v_pk_mul_f32 v[148:149], v[144:145], v[230:231]
	v_pk_mul_f32 v[150:151], v[146:147], v[232:233]
	v_pk_add_f32 v[234:235], v[88:89], 1.0 op_sel_hi:[1,0] neg_lo:[1,0] neg_hi:[1,0]
	v_pk_add_f32 v[236:237], v[90:91], 1.0 op_sel_hi:[1,0] neg_lo:[1,0] neg_hi:[1,0]
	v_pk_mul_f32 v[152:153], v[148:149], v[234:235]
	v_pk_mul_f32 v[154:155], v[150:151], v[236:237]
	v_pk_add_f32 v[238:239], v[92:93], 1.0 op_sel_hi:[1,0] neg_lo:[1,0] neg_hi:[1,0]
	v_pk_add_f32 v[240:241], v[94:95], 1.0 op_sel_hi:[1,0] neg_lo:[1,0] neg_hi:[1,0]
	v_pk_mul_f32 v[156:157], v[152:153], v[238:239]
	v_pk_mul_f32 v[158:159], v[154:155], v[240:241]
	v_pk_add_f32 v[242:243], v[96:97], 1.0 op_sel_hi:[1,0] neg_lo:[1,0] neg_hi:[1,0]
	v_pk_add_f32 v[244:245], v[98:99], 1.0 op_sel_hi:[1,0] neg_lo:[1,0] neg_hi:[1,0]
	v_pk_mul_f32 v[160:161], v[156:157], v[242:243]
	v_pk_mul_f32 v[162:163], v[158:159], v[244:245]
	v_pk_add_f32 v[246:247], v[100:101], 1.0 op_sel_hi:[1,0] neg_lo:[1,0] neg_hi:[1,0]
	v_pk_add_f32 v[248:249], v[102:103], 1.0 op_sel_hi:[1,0] neg_lo:[1,0] neg_hi:[1,0]
	v_pk_mul_f32 v[164:165], v[160:161], v[246:247]
	v_pk_mul_f32 v[166:167], v[162:163], v[248:249]
	v_pk_add_f32 v[74:75], v[104:105], 1.0 op_sel_hi:[1,0] neg_lo:[1,0] neg_hi:[1,0]
	v_pk_add_f32 v[172:173], v[106:107], 1.0 op_sel_hi:[1,0] neg_lo:[1,0] neg_hi:[1,0]
	v_pk_mul_f32 v[168:169], v[164:165], v[74:75]
	v_pk_mul_f32 v[170:171], v[166:167], v[172:173]
	s_waitcnt lgkmcnt(0)
	s_barrier
	s_mov_b32 s17, 31
.Lhg_ploop:
	v_lshlrev_b32_e32 v108, 16, v58
	v_and_b32_e32 v109, 0xffff0000, v58
	v_lshlrev_b32_e32 v110, 16, v59
	v_and_b32_e32 v111, 0xffff0000, v59
	v_lshlrev_b32_e32 v112, 16, v60
	v_and_b32_e32 v113, 0xffff0000, v60
	v_lshlrev_b32_e32 v114, 16, v61
	v_and_b32_e32 v115, 0xffff0000, v61
	v_lshlrev_b32_e32 v116, 16, v62
	v_and_b32_e32 v117, 0xffff0000, v62
	v_lshlrev_b32_e32 v118, 16, v63
	v_and_b32_e32 v119, 0xffff0000, v63
	v_lshlrev_b32_e32 v120, 16, v64
	v_and_b32_e32 v121, 0xffff0000, v64
	v_lshlrev_b32_e32 v122, 16, v65
	v_and_b32_e32 v123, 0xffff0000, v65
	v_lshlrev_b32_e32 v124, 16, v66
	v_and_b32_e32 v125, 0xffff0000, v66
	v_lshlrev_b32_e32 v126, 16, v67
	v_and_b32_e32 v127, 0xffff0000, v67
	v_lshlrev_b32_e32 v128, 16, v68
	v_and_b32_e32 v129, 0xffff0000, v68
	v_lshlrev_b32_e32 v130, 16, v69
	v_and_b32_e32 v131, 0xffff0000, v69
	v_lshlrev_b32_e32 v132, 16, v70
	v_and_b32_e32 v133, 0xffff0000, v70
	v_lshlrev_b32_e32 v134, 16, v71
	v_and_b32_e32 v135, 0xffff0000, v71
	v_lshlrev_b32_e32 v136, 16, v72
	v_and_b32_e32 v137, 0xffff0000, v72
	v_lshlrev_b32_e32 v138, 16, v73
	v_and_b32_e32 v139, 0xffff0000, v73
	global_load_dwordx2 v[42:43], v3, s[8:9]
	global_load_dwordx2 v[58:59], v2, s[8:9]
	s_add_u32 s8, s8, s10
	s_addc_u32 s9, s9, s11
	global_load_dwordx2 v[44:45], v3, s[8:9]
	global_load_dwordx2 v[60:61], v2, s[8:9]
	s_add_u32 s8, s8, s10
	s_addc_u32 s9, s9, s11
	global_load_dwordx2 v[46:47], v3, s[8:9]
	global_load_dwordx2 v[62:63], v2, s[8:9]
	s_add_u32 s8, s8, s10
	s_addc_u32 s9, s9, s11
	global_load_dwordx2 v[48:49], v3, s[8:9]
	global_load_dwordx2 v[64:65], v2, s[8:9]
	s_add_u32 s8, s8, s10
	s_addc_u32 s9, s9, s11
	global_load_dwordx2 v[50:51], v3, s[8:9]
	global_load_dwordx2 v[66:67], v2, s[8:9]
	s_add_u32 s8, s8, s10
	s_addc_u32 s9, s9, s11
	global_load_dwordx2 v[52:53], v3, s[8:9]
	global_load_dwordx2 v[68:69], v2, s[8:9]
	s_add_u32 s8, s8, s10
	s_addc_u32 s9, s9, s11
	global_load_dwordx2 v[54:55], v3, s[8:9]
	global_load_dwordx2 v[70:71], v2, s[8:9]
	s_add_u32 s8, s8, s10
	s_addc_u32 s9, s9, s11
	global_load_dwordx2 v[56:57], v3, s[8:9]
	global_load_dwordx2 v[72:73], v2, s[8:9]
	s_add_u32 s8, s8, s10
	s_addc_u32 s9, s9, s11
	s_cmp_lt_u32 s16, 63
	s_cselect_b32 s34, s12, s14
	s_cselect_b32 s35, s13, s15
	s_add_u32 s8, s8, s34
	s_addc_u32 s9, s9, s35
	s_add_i32 s16, s16, 1
	v_mov_b32_e32 v192, 1.0
	v_mov_b32_e32 v193, 1.0
	v_mov_b32_e32 v194, 1.0
	v_mov_b32_e32 v195, 1.0
	v_mov_b32_dpp v192, v168 row_shr:8 row_mask:0xf bank_mask:0xc
	v_mov_b32_dpp v193, v169 row_shr:8 row_mask:0xf bank_mask:0xc
	v_mov_b32_dpp v194, v170 row_shr:8 row_mask:0xf bank_mask:0xc
	v_mov_b32_dpp v195, v171 row_shr:8 row_mask:0xf bank_mask:0xc
	v_mul_f32_dpp v196, v168, v168 row_ror:8 row_mask:0xf bank_mask:0xf
	v_mul_f32_dpp v197, v169, v169 row_ror:8 row_mask:0xf bank_mask:0xf
	v_mul_f32_dpp v198, v170, v170 row_ror:8 row_mask:0xf bank_mask:0xf
	v_mul_f32_dpp v199, v171, v171 row_ror:8 row_mask:0xf bank_mask:0xf
	v_mov_b32_e32 v200, v196
	v_mov_b32_e32 v201, v197
	v_mov_b32_e32 v202, v198
	v_mov_b32_e32 v203, v199
	v_permlane16_swap_b32_e32 v196, v200
	v_permlane16_swap_b32_e32 v197, v201
	v_permlane16_swap_b32_e32 v198, v202
	v_permlane16_swap_b32_e32 v199, v203
	v_pk_mul_f32 v[204:205], v[196:197], v[200:201]
	v_pk_mul_f32 v[206:207], v[198:199], v[202:203]
	v_mov_b32_e32 v208, v204
	v_mov_b32_e32 v209, v205
	v_mov_b32_e32 v210, v206
	v_mov_b32_e32 v211, v207
	v_mov_b32_e32 v212, 1.0
	v_mov_b32_e32 v213, 1.0
	v_mov_b32_e32 v214, 1.0
	v_mov_b32_e32 v215, 1.0
	v_permlane32_swap_b32_e32 v204, v208
	v_permlane32_swap_b32_e32 v205, v209
	v_permlane32_swap_b32_e32 v206, v210
	v_permlane32_swap_b32_e32 v207, v211
	s_mov_b64 s[34:35], exec
	s_mov_b64 exec, 0xffff0000
	v_mov_b32_e32 v212, v196
	v_mov_b32_e32 v213, v197
	v_mov_b32_e32 v214, v198
	v_mov_b32_e32 v215, v199
	s_mov_b32 exec_lo, 0
	s_mov_b32 exec_hi, -1
	v_mov_b32_e32 v212, v204
	v_mov_b32_e32 v213, v205
	v_mov_b32_e32 v214, v206
	v_mov_b32_e32 v215, v207
	s_mov_b32 exec_hi, 0xffff0000
	v_pk_mul_f32 v[212:213], v[212:213], v[196:197]
	v_pk_mul_f32 v[214:215], v[214:215], v[198:199]
	s_mov_b64 exec, s[34:35]
	v_pk_mul_f32 v[176:177], v[212:213], v[192:193]
	v_pk_mul_f32 v[178:179], v[214:215], v[194:195]
	v_pk_mul_f32 v[188:189], v[176:177], v[168:169]
	v_pk_mul_f32 v[190:191], v[178:179], v[170:171]
	s_mov_b64 s[34:35], exec
	s_mov_b64 exec, s[30:31]
	ds_write_b128 v8, v[188:191] offset:512
	s_mov_b64 exec, s[34:35]
	v_max_f32_e32 v180, 0xda24260, v188
	v_max_f32_e32 v181, 0xda24260, v189
	v_max_f32_e32 v182, 0xda24260, v190
	v_max_f32_e32 v183, 0xda24260, v191
	v_rcp_f32_e32 v180, v180
	v_rcp_f32_e32 v181, v181
	v_rcp_f32_e32 v182, v182
	v_rcp_f32_e32 v183, v183
	v_pk_mul_f32 v[192:193], v[136:137], v[188:189]
	v_pk_mul_f32 v[194:195], v[138:139], v[190:191]
	v_pk_mul_f32 v[196:197], v[104:105], v[180:181]
	v_pk_mul_f32 v[198:199], v[106:107], v[182:183]
	v_cvt_pk_bf16_f32 v204, v192, v193
	v_cvt_pk_bf16_f32 v205, v194, v195
	ds_write_b64 v4, v[204:205] offset:20448
	v_cvt_pk_bf16_f32 v206, v196, v197
	v_cvt_pk_bf16_f32 v207, v198, v199
	ds_write_b64 v4, v[206:207] offset:57312
	v_pk_mul_f32 v[180:181], v[180:181], v[74:75]
	v_pk_mul_f32 v[182:183], v[182:183], v[172:173]
	v_pk_mul_f32 v[188:189], v[176:177], v[164:165]
	v_pk_mul_f32 v[190:191], v[178:179], v[166:167]
	v_pk_mul_f32 v[192:193], v[132:133], v[188:189]
	v_pk_mul_f32 v[194:195], v[134:135], v[190:191]
	v_pk_mul_f32 v[200:201], v[100:101], v[180:181]
	v_pk_mul_f32 v[202:203], v[102:103], v[182:183]
	v_cvt_pk_bf16_f32 v204, v192, v193
	v_cvt_pk_bf16_f32 v205, v194, v195
	ds_write_b64 v4, v[204:205] offset:20160
	v_cvt_pk_bf16_f32 v206, v200, v201
	v_cvt_pk_bf16_f32 v207, v202, v203
	ds_write_b64 v4, v[206:207] offset:57024
	v_pk_mul_f32 v[180:181], v[180:181], v[246:247]
	v_pk_mul_f32 v[182:183], v[182:183], v[248:249]
	v_pk_mul_f32 v[188:189], v[176:177], v[160:161]
	v_pk_mul_f32 v[190:191], v[178:179], v[162:163]
	v_pk_mul_f32 v[192:193], v[128:129], v[188:189]
	v_pk_mul_f32 v[194:195], v[130:131], v[190:191]
	v_pk_mul_f32 v[196:197], v[96:97], v[180:181]
	v_pk_mul_f32 v[198:199], v[98:99], v[182:183]
	v_cvt_pk_bf16_f32 v204, v192, v193
	v_cvt_pk_bf16_f32 v205, v194, v195
	ds_write_b64 v4, v[204:205] offset:19872
	v_cvt_pk_bf16_f32 v206, v196, v197
	v_cvt_pk_bf16_f32 v207, v198, v199
	ds_write_b64 v4, v[206:207] offset:56736
	v_pk_mul_f32 v[180:181], v[180:181], v[242:243]
	v_pk_mul_f32 v[182:183], v[182:183], v[244:245]
	v_pk_mul_f32 v[188:189], v[176:177], v[156:157]
	v_pk_mul_f32 v[190:191], v[178:179], v[158:159]
	v_pk_mul_f32 v[192:193], v[124:125], v[188:189]
	v_pk_mul_f32 v[194:195], v[126:127], v[190:191]
	v_pk_mul_f32 v[200:201], v[92:93], v[180:181]
	v_pk_mul_f32 v[202:203], v[94:95], v[182:183]
	v_cvt_pk_bf16_f32 v204, v192, v193
	v_cvt_pk_bf16_f32 v205, v194, v195
	ds_write_b64 v4, v[204:205] offset:19584
	v_cvt_pk_bf16_f32 v206, v200, v201
	v_cvt_pk_bf16_f32 v207, v202, v203
	ds_write_b64 v4, v[206:207] offset:56448
	v_pk_mul_f32 v[180:181], v[180:181], v[238:239]
	v_pk_mul_f32 v[182:183], v[182:183], v[240:241]
	v_pk_mul_f32 v[188:189], v[176:177], v[152:153]
	v_pk_mul_f32 v[190:191], v[178:179], v[154:155]
	v_pk_mul_f32 v[192:193], v[120:121], v[188:189]
	v_pk_mul_f32 v[194:195], v[122:123], v[190:191]
	v_pk_mul_f32 v[196:197], v[88:89], v[180:181]
	v_pk_mul_f32 v[198:199], v[90:91], v[182:183]
	v_cvt_pk_bf16_f32 v204, v192, v193
	v_cvt_pk_bf16_f32 v205, v194, v195
	ds_write_b64 v4, v[204:205] offset:19296
	v_cvt_pk_bf16_f32 v206, v196, v197
	v_cvt_pk_bf16_f32 v207, v198, v199
	ds_write_b64 v4, v[206:207] offset:56160
	v_pk_mul_f32 v[180:181], v[180:181], v[234:235]
	v_pk_mul_f32 v[182:183], v[182:183], v[236:237]
	v_pk_mul_f32 v[188:189], v[176:177], v[148:149]
	v_pk_mul_f32 v[190:191], v[178:179], v[150:151]
	v_pk_mul_f32 v[192:193], v[116:117], v[188:189]
	v_pk_mul_f32 v[194:195], v[118:119], v[190:191]
	v_pk_mul_f32 v[200:201], v[84:85], v[180:181]
	v_pk_mul_f32 v[202:203], v[86:87], v[182:183]
	v_cvt_pk_bf16_f32 v204, v192, v193
	v_cvt_pk_bf16_f32 v205, v194, v195
	ds_write_b64 v4, v[204:205] offset:19008
	v_cvt_pk_bf16_f32 v206, v200, v201
	v_cvt_pk_bf16_f32 v207, v202, v203
	ds_write_b64 v4, v[206:207] offset:55872
	v_pk_mul_f32 v[180:181], v[180:181], v[230:231]
	v_pk_mul_f32 v[182:183], v[182:183], v[232:233]
	v_pk_mul_f32 v[188:189], v[176:177], v[144:145]
	v_pk_mul_f32 v[190:191], v[178:179], v[146:147]
	v_pk_mul_f32 v[192:193], v[112:113], v[188:189]
	v_pk_mul_f32 v[194:195], v[114:115], v[190:191]
	v_pk_mul_f32 v[196:197], v[80:81], v[180:181]
	v_pk_mul_f32 v[198:199], v[82:83], v[182:183]
	v_cvt_pk_bf16_f32 v204, v192, v193
	v_cvt_pk_bf16_f32 v205, v194, v195
	ds_write_b64 v4, v[204:205] offset:18720
	v_cvt_pk_bf16_f32 v206, v196, v197
	v_cvt_pk_bf16_f32 v207, v198, v199
	ds_write_b64 v4, v[206:207] offset:55584
	v_pk_mul_f32 v[180:181], v[180:181], v[226:227]
	v_pk_mul_f32 v[182:183], v[182:183], v[228:229]
	v_pk_mul_f32 v[188:189], v[176:177], v[140:141]
	v_pk_mul_f32 v[190:191], v[178:179], v[142:143]
	v_pk_mul_f32 v[192:193], v[108:109], v[188:189]
	v_pk_mul_f32 v[194:195], v[110:111], v[190:191]
	v_pk_mul_f32 v[200:201], v[76:77], v[180:181]
	v_pk_mul_f32 v[202:203], v[78:79], v[182:183]
	v_cvt_pk_bf16_f32 v204, v192, v193
	v_cvt_pk_bf16_f32 v205, v194, v195
	ds_write_b64 v4, v[204:205] offset:18432
	v_cvt_pk_bf16_f32 v206, v200, v201
	v_cvt_pk_bf16_f32 v207, v202, v203
	ds_write_b64 v4, v[206:207] offset:55296
	s_waitcnt vmcnt(16)
	v_lshlrev_b32_e32 v76, 16, v10
	v_and_b32_e32 v77, 0xffff0000, v10
	v_lshlrev_b32_e32 v78, 16, v11
	v_and_b32_e32 v79, 0xffff0000, v11
	v_lshlrev_b32_e32 v80, 16, v12
	v_and_b32_e32 v81, 0xffff0000, v12
	v_lshlrev_b32_e32 v82, 16, v13
	v_and_b32_e32 v83, 0xffff0000, v13
	v_lshlrev_b32_e32 v84, 16, v14
	v_and_b32_e32 v85, 0xffff0000, v14
	v_lshlrev_b32_e32 v86, 16, v15
	v_and_b32_e32 v87, 0xffff0000, v15
	v_lshlrev_b32_e32 v88, 16, v16
	v_and_b32_e32 v89, 0xffff0000, v16
	v_lshlrev_b32_e32 v90, 16, v17
	v_and_b32_e32 v91, 0xffff0000, v17
	v_lshlrev_b32_e32 v92, 16, v18
	v_and_b32_e32 v93, 0xffff0000, v18
	v_lshlrev_b32_e32 v94, 16, v19
	v_and_b32_e32 v95, 0xffff0000, v19
	v_lshlrev_b32_e32 v96, 16, v20
	v_and_b32_e32 v97, 0xffff0000, v20
	v_lshlrev_b32_e32 v98, 16, v21
	v_and_b32_e32 v99, 0xffff0000, v21
	v_lshlrev_b32_e32 v100, 16, v22
	v_and_b32_e32 v101, 0xffff0000, v22
	v_lshlrev_b32_e32 v102, 16, v23
	v_and_b32_e32 v103, 0xffff0000, v23
	v_lshlrev_b32_e32 v104, 16, v24
	v_and_b32_e32 v105, 0xffff0000, v24
	v_lshlrev_b32_e32 v106, 16, v25
	v_and_b32_e32 v107, 0xffff0000, v25
	v_pk_add_f32 v[140:141], v[76:77], 1.0 op_sel_hi:[1,0] neg_lo:[1,0] neg_hi:[1,0]
	v_pk_add_f32 v[142:143], v[78:79], 1.0 op_sel_hi:[1,0] neg_lo:[1,0] neg_hi:[1,0]
	v_pk_add_f32 v[226:227], v[80:81], 1.0 op_sel_hi:[1,0] neg_lo:[1,0] neg_hi:[1,0]
	v_pk_add_f32 v[228:229], v[82:83], 1.0 op_sel_hi:[1,0] neg_lo:[1,0] neg_hi:[1,0]
	v_pk_mul_f32 v[144:145], v[140:141], v[226:227]
	v_pk_mul_f32 v[146:147], v[142:143], v[228:229]
	v_pk_add_f32 v[230:231], v[84:85], 1.0 op_sel_hi:[1,0] neg_lo:[1,0] neg_hi:[1,0]
	v_pk_add_f32 v[232:233], v[86:87], 1.0 op_sel_hi:[1,0] neg_lo:[1,0] neg_hi:[1,0]
	v_pk_mul_f32 v[148:149], v[144:145], v[230:231]
	v_pk_mul_f32 v[150:151], v[146:147], v[232:233]
	v_pk_add_f32 v[234:235], v[88:89], 1.0 op_sel_hi:[1,0] neg_lo:[1,0] neg_hi:[1,0]
	v_pk_add_f32 v[236:237], v[90:91], 1.0 op_sel_hi:[1,0] neg_lo:[1,0] neg_hi:[1,0]
	v_pk_mul_f32 v[152:153], v[148:149], v[234:235]
	v_pk_mul_f32 v[154:155], v[150:151], v[236:237]
	v_pk_add_f32 v[238:239], v[92:93], 1.0 op_sel_hi:[1,0] neg_lo:[1,0] neg_hi:[1,0]
	v_pk_add_f32 v[240:241], v[94:95], 1.0 op_sel_hi:[1,0] neg_lo:[1,0] neg_hi:[1,0]
	v_pk_mul_f32 v[156:157], v[152:153], v[238:239]
	v_pk_mul_f32 v[158:159], v[154:155], v[240:241]
	v_pk_add_f32 v[242:243], v[96:97], 1.0 op_sel_hi:[1,0] neg_lo:[1,0] neg_hi:[1,0]
	v_pk_add_f32 v[244:245], v[98:99], 1.0 op_sel_hi:[1,0] neg_lo:[1,0] neg_hi:[1,0]
	v_pk_mul_f32 v[160:161], v[156:157], v[242:243]
	v_pk_mul_f32 v[162:163], v[158:159], v[244:245]
	v_pk_add_f32 v[246:247], v[100:101], 1.0 op_sel_hi:[1,0] neg_lo:[1,0] neg_hi:[1,0]
	v_pk_add_f32 v[248:249], v[102:103], 1.0 op_sel_hi:[1,0] neg_lo:[1,0] neg_hi:[1,0]
	v_pk_mul_f32 v[164:165], v[160:161], v[246:247]
	v_pk_mul_f32 v[166:167], v[162:163], v[248:249]
	v_pk_add_f32 v[74:75], v[104:105], 1.0 op_sel_hi:[1,0] neg_lo:[1,0] neg_hi:[1,0]
	v_pk_add_f32 v[172:173], v[106:107], 1.0 op_sel_hi:[1,0] neg_lo:[1,0] neg_hi:[1,0]
	v_pk_mul_f32 v[168:169], v[164:165], v[74:75]
	v_pk_mul_f32 v[170:171], v[166:167], v[172:173]
	s_waitcnt lgkmcnt(0)
	s_barrier
	s_cmp_eq_u32 s17, 0
	s_cbranch_scc1 .Lhg_pend
	v_lshlrev_b32_e32 v108, 16, v26
	v_and_b32_e32 v109, 0xffff0000, v26
	v_lshlrev_b32_e32 v110, 16, v27
	v_and_b32_e32 v111, 0xffff0000, v27
	v_lshlrev_b32_e32 v112, 16, v28
	v_and_b32_e32 v113, 0xffff0000, v28
	v_lshlrev_b32_e32 v114, 16, v29
	v_and_b32_e32 v115, 0xffff0000, v29
	v_lshlrev_b32_e32 v116, 16, v30
	v_and_b32_e32 v117, 0xffff0000, v30
	v_lshlrev_b32_e32 v118, 16, v31
	v_and_b32_e32 v119, 0xffff0000, v31
	v_lshlrev_b32_e32 v120, 16, v32
	v_and_b32_e32 v121, 0xffff0000, v32
	v_lshlrev_b32_e32 v122, 16, v33
	v_and_b32_e32 v123, 0xffff0000, v33
	v_lshlrev_b32_e32 v124, 16, v34
	v_and_b32_e32 v125, 0xffff0000, v34
	v_lshlrev_b32_e32 v126, 16, v35
	v_and_b32_e32 v127, 0xffff0000, v35
	v_lshlrev_b32_e32 v128, 16, v36
	v_and_b32_e32 v129, 0xffff0000, v36
	v_lshlrev_b32_e32 v130, 16, v37
	v_and_b32_e32 v131, 0xffff0000, v37
	v_lshlrev_b32_e32 v132, 16, v38
	v_and_b32_e32 v133, 0xffff0000, v38
	v_lshlrev_b32_e32 v134, 16, v39
	v_and_b32_e32 v135, 0xffff0000, v39
	v_lshlrev_b32_e32 v136, 16, v40
	v_and_b32_e32 v137, 0xffff0000, v40
	v_lshlrev_b32_e32 v138, 16, v41
	v_and_b32_e32 v139, 0xffff0000, v41
	global_load_dwordx2 v[10:11], v3, s[8:9]
	global_load_dwordx2 v[26:27], v2, s[8:9]
	s_add_u32 s8, s8, s10
	s_addc_u32 s9, s9, s11
	global_load_dwordx2 v[12:13], v3, s[8:9]
	global_load_dwordx2 v[28:29], v2, s[8:9]
	s_add_u32 s8, s8, s10
	s_addc_u32 s9, s9, s11
	global_load_dwordx2 v[14:15], v3, s[8:9]
	global_load_dwordx2 v[30:31], v2, s[8:9]
	s_add_u32 s8, s8, s10
	s_addc_u32 s9, s9, s11
	global_load_dwordx2 v[16:17], v3, s[8:9]
	global_load_dwordx2 v[32:33], v2, s[8:9]
	s_add_u32 s8, s8, s10
	s_addc_u32 s9, s9, s11
	global_load_dwordx2 v[18:19], v3, s[8:9]
	global_load_dwordx2 v[34:35], v2, s[8:9]
	s_add_u32 s8, s8, s10
	s_addc_u32 s9, s9, s11
	global_load_dwordx2 v[20:21], v3, s[8:9]
	global_load_dwordx2 v[36:37], v2, s[8:9]
	s_add_u32 s8, s8, s10
	s_addc_u32 s9, s9, s11
	global_load_dwordx2 v[22:23], v3, s[8:9]
	global_load_dwordx2 v[38:39], v2, s[8:9]
	s_add_u32 s8, s8, s10
	s_addc_u32 s9, s9, s11
	global_load_dwordx2 v[24:25], v3, s[8:9]
	global_load_dwordx2 v[40:41], v2, s[8:9]
	s_add_u32 s8, s8, s10
	s_addc_u32 s9, s9, s11
	s_cmp_lt_u32 s16, 63
	s_cselect_b32 s34, s12, s14
	s_cselect_b32 s35, s13, s15
	s_add_u32 s8, s8, s34
	s_addc_u32 s9, s9, s35
	s_add_i32 s16, s16, 1
	v_mov_b32_e32 v192, 1.0
	v_mov_b32_e32 v193, 1.0
	v_mov_b32_e32 v194, 1.0
	v_mov_b32_e32 v195, 1.0
	v_mov_b32_dpp v192, v168 row_shr:8 row_mask:0xf bank_mask:0xc
	v_mov_b32_dpp v193, v169 row_shr:8 row_mask:0xf bank_mask:0xc
	v_mov_b32_dpp v194, v170 row_shr:8 row_mask:0xf bank_mask:0xc
	v_mov_b32_dpp v195, v171 row_shr:8 row_mask:0xf bank_mask:0xc
	v_mul_f32_dpp v196, v168, v168 row_ror:8 row_mask:0xf bank_mask:0xf
	v_mul_f32_dpp v197, v169, v169 row_ror:8 row_mask:0xf bank_mask:0xf
	v_mul_f32_dpp v198, v170, v170 row_ror:8 row_mask:0xf bank_mask:0xf
	v_mul_f32_dpp v199, v171, v171 row_ror:8 row_mask:0xf bank_mask:0xf
	v_mov_b32_e32 v200, v196
	v_mov_b32_e32 v201, v197
	v_mov_b32_e32 v202, v198
	v_mov_b32_e32 v203, v199
	v_permlane16_swap_b32_e32 v196, v200
	v_permlane16_swap_b32_e32 v197, v201
	v_permlane16_swap_b32_e32 v198, v202
	v_permlane16_swap_b32_e32 v199, v203
	v_pk_mul_f32 v[204:205], v[196:197], v[200:201]
	v_pk_mul_f32 v[206:207], v[198:199], v[202:203]
	v_mov_b32_e32 v208, v204
	v_mov_b32_e32 v209, v205
	v_mov_b32_e32 v210, v206
	v_mov_b32_e32 v211, v207
	v_mov_b32_e32 v212, 1.0
	v_mov_b32_e32 v213, 1.0
	v_mov_b32_e32 v214, 1.0
	v_mov_b32_e32 v215, 1.0
	v_permlane32_swap_b32_e32 v204, v208
	v_permlane32_swap_b32_e32 v205, v209
	v_permlane32_swap_b32_e32 v206, v210
	v_permlane32_swap_b32_e32 v207, v211
	s_mov_b64 s[34:35], exec
	s_mov_b64 exec, 0xffff0000
	v_mov_b32_e32 v212, v196
	v_mov_b32_e32 v213, v197
	v_mov_b32_e32 v214, v198
	v_mov_b32_e32 v215, v199
	s_mov_b32 exec_lo, 0
	s_mov_b32 exec_hi, -1
	v_mov_b32_e32 v212, v204
	v_mov_b32_e32 v213, v205
	v_mov_b32_e32 v214, v206
	v_mov_b32_e32 v215, v207
	s_mov_b32 exec_hi, 0xffff0000
	v_pk_mul_f32 v[212:213], v[212:213], v[196:197]
	v_pk_mul_f32 v[214:215], v[214:215], v[198:199]
	s_mov_b64 exec, s[34:35]
	v_pk_mul_f32 v[176:177], v[212:213], v[192:193]
	v_pk_mul_f32 v[178:179], v[214:215], v[194:195]
	v_pk_mul_f32 v[188:189], v[176:177], v[168:169]
	v_pk_mul_f32 v[190:191], v[178:179], v[170:171]
	s_mov_b64 s[34:35], exec
	s_mov_b64 exec, s[30:31]
	ds_write_b128 v8, v[188:191]
	s_mov_b64 exec, s[34:35]
	v_max_f32_e32 v180, 0xda24260, v188
	v_max_f32_e32 v181, 0xda24260, v189
	v_max_f32_e32 v182, 0xda24260, v190
	v_max_f32_e32 v183, 0xda24260, v191
	v_rcp_f32_e32 v180, v180
	v_rcp_f32_e32 v181, v181
	v_rcp_f32_e32 v182, v182
	v_rcp_f32_e32 v183, v183
	v_pk_mul_f32 v[192:193], v[136:137], v[188:189]
	v_pk_mul_f32 v[194:195], v[138:139], v[190:191]
	v_pk_mul_f32 v[196:197], v[104:105], v[180:181]
	v_pk_mul_f32 v[198:199], v[106:107], v[182:183]
	v_cvt_pk_bf16_f32 v204, v192, v193
	v_cvt_pk_bf16_f32 v205, v194, v195
	ds_write_b64 v4, v[204:205] offset:2016
	v_cvt_pk_bf16_f32 v206, v196, v197
	v_cvt_pk_bf16_f32 v207, v198, v199
	ds_write_b64 v4, v[206:207] offset:38880
	v_pk_mul_f32 v[180:181], v[180:181], v[74:75]
	v_pk_mul_f32 v[182:183], v[182:183], v[172:173]
	v_pk_mul_f32 v[188:189], v[176:177], v[164:165]
	v_pk_mul_f32 v[190:191], v[178:179], v[166:167]
	v_pk_mul_f32 v[192:193], v[132:133], v[188:189]
	v_pk_mul_f32 v[194:195], v[134:135], v[190:191]
	v_pk_mul_f32 v[200:201], v[100:101], v[180:181]
	v_pk_mul_f32 v[202:203], v[102:103], v[182:183]
	v_cvt_pk_bf16_f32 v204, v192, v193
	v_cvt_pk_bf16_f32 v205, v194, v195
	ds_write_b64 v4, v[204:205] offset:1728
	v_cvt_pk_bf16_f32 v206, v200, v201
	v_cvt_pk_bf16_f32 v207, v202, v203
	ds_write_b64 v4, v[206:207] offset:38592
	v_pk_mul_f32 v[180:181], v[180:181], v[246:247]
	v_pk_mul_f32 v[182:183], v[182:183], v[248:249]
	v_pk_mul_f32 v[188:189], v[176:177], v[160:161]
	v_pk_mul_f32 v[190:191], v[178:179], v[162:163]
	v_pk_mul_f32 v[192:193], v[128:129], v[188:189]
	v_pk_mul_f32 v[194:195], v[130:131], v[190:191]
	v_pk_mul_f32 v[196:197], v[96:97], v[180:181]
	v_pk_mul_f32 v[198:199], v[98:99], v[182:183]
	v_cvt_pk_bf16_f32 v204, v192, v193
	v_cvt_pk_bf16_f32 v205, v194, v195
	ds_write_b64 v4, v[204:205] offset:1440
	v_cvt_pk_bf16_f32 v206, v196, v197
	v_cvt_pk_bf16_f32 v207, v198, v199
	ds_write_b64 v4, v[206:207] offset:38304
	v_pk_mul_f32 v[180:181], v[180:181], v[242:243]
	v_pk_mul_f32 v[182:183], v[182:183], v[244:245]
	v_pk_mul_f32 v[188:189], v[176:177], v[156:157]
	v_pk_mul_f32 v[190:191], v[178:179], v[158:159]
	v_pk_mul_f32 v[192:193], v[124:125], v[188:189]
	v_pk_mul_f32 v[194:195], v[126:127], v[190:191]
	v_pk_mul_f32 v[200:201], v[92:93], v[180:181]
	v_pk_mul_f32 v[202:203], v[94:95], v[182:183]
	v_cvt_pk_bf16_f32 v204, v192, v193
	v_cvt_pk_bf16_f32 v205, v194, v195
	ds_write_b64 v4, v[204:205] offset:1152
	v_cvt_pk_bf16_f32 v206, v200, v201
	v_cvt_pk_bf16_f32 v207, v202, v203
	ds_write_b64 v4, v[206:207] offset:38016
	v_pk_mul_f32 v[180:181], v[180:181], v[238:239]
	v_pk_mul_f32 v[182:183], v[182:183], v[240:241]
	v_pk_mul_f32 v[188:189], v[176:177], v[152:153]
	v_pk_mul_f32 v[190:191], v[178:179], v[154:155]
	v_pk_mul_f32 v[192:193], v[120:121], v[188:189]
	v_pk_mul_f32 v[194:195], v[122:123], v[190:191]
	v_pk_mul_f32 v[196:197], v[88:89], v[180:181]
	v_pk_mul_f32 v[198:199], v[90:91], v[182:183]
	v_cvt_pk_bf16_f32 v204, v192, v193
	v_cvt_pk_bf16_f32 v205, v194, v195
	ds_write_b64 v4, v[204:205] offset:864
	v_cvt_pk_bf16_f32 v206, v196, v197
	v_cvt_pk_bf16_f32 v207, v198, v199
	ds_write_b64 v4, v[206:207] offset:37728
	v_pk_mul_f32 v[180:181], v[180:181], v[234:235]
	v_pk_mul_f32 v[182:183], v[182:183], v[236:237]
	v_pk_mul_f32 v[188:189], v[176:177], v[148:149]
	v_pk_mul_f32 v[190:191], v[178:179], v[150:151]
	v_pk_mul_f32 v[192:193], v[116:117], v[188:189]
	v_pk_mul_f32 v[194:195], v[118:119], v[190:191]
	v_pk_mul_f32 v[200:201], v[84:85], v[180:181]
	v_pk_mul_f32 v[202:203], v[86:87], v[182:183]
	v_cvt_pk_bf16_f32 v204, v192, v193
	v_cvt_pk_bf16_f32 v205, v194, v195
	ds_write_b64 v4, v[204:205] offset:576
	v_cvt_pk_bf16_f32 v206, v200, v201
	v_cvt_pk_bf16_f32 v207, v202, v203
	ds_write_b64 v4, v[206:207] offset:37440
	v_pk_mul_f32 v[180:181], v[180:181], v[230:231]
	v_pk_mul_f32 v[182:183], v[182:183], v[232:233]
	v_pk_mul_f32 v[188:189], v[176:177], v[144:145]
	v_pk_mul_f32 v[190:191], v[178:179], v[146:147]
	v_pk_mul_f32 v[192:193], v[112:113], v[188:189]
	v_pk_mul_f32 v[194:195], v[114:115], v[190:191]
	v_pk_mul_f32 v[196:197], v[80:81], v[180:181]
	v_pk_mul_f32 v[198:199], v[82:83], v[182:183]
	v_cvt_pk_bf16_f32 v204, v192, v193
	v_cvt_pk_bf16_f32 v205, v194, v195
	ds_write_b64 v4, v[204:205] offset:288
	v_cvt_pk_bf16_f32 v206, v196, v197
	v_cvt_pk_bf16_f32 v207, v198, v199
	ds_write_b64 v4, v[206:207] offset:37152
	v_pk_mul_f32 v[180:181], v[180:181], v[226:227]
	v_pk_mul_f32 v[182:183], v[182:183], v[228:229]
	v_pk_mul_f32 v[188:189], v[176:177], v[140:141]
	v_pk_mul_f32 v[190:191], v[178:179], v[142:143]
	v_pk_mul_f32 v[192:193], v[108:109], v[188:189]
	v_pk_mul_f32 v[194:195], v[110:111], v[190:191]
	v_pk_mul_f32 v[200:201], v[76:77], v[180:181]
	v_pk_mul_f32 v[202:203], v[78:79], v[182:183]
	v_cvt_pk_bf16_f32 v204, v192, v193
	v_cvt_pk_bf16_f32 v205, v194, v195
	ds_write_b64 v4, v[204:205]
	v_cvt_pk_bf16_f32 v206, v200, v201
	v_cvt_pk_bf16_f32 v207, v202, v203
	ds_write_b64 v4, v[206:207] offset:36864
	s_waitcnt vmcnt(16)
	v_lshlrev_b32_e32 v76, 16, v42
	v_and_b32_e32 v77, 0xffff0000, v42
	v_lshlrev_b32_e32 v78, 16, v43
	v_and_b32_e32 v79, 0xffff0000, v43
	v_lshlrev_b32_e32 v80, 16, v44
	v_and_b32_e32 v81, 0xffff0000, v44
	v_lshlrev_b32_e32 v82, 16, v45
	v_and_b32_e32 v83, 0xffff0000, v45
	v_lshlrev_b32_e32 v84, 16, v46
	v_and_b32_e32 v85, 0xffff0000, v46
	v_lshlrev_b32_e32 v86, 16, v47
	v_and_b32_e32 v87, 0xffff0000, v47
	v_lshlrev_b32_e32 v88, 16, v48
	v_and_b32_e32 v89, 0xffff0000, v48
	v_lshlrev_b32_e32 v90, 16, v49
	v_and_b32_e32 v91, 0xffff0000, v49
	v_lshlrev_b32_e32 v92, 16, v50
	v_and_b32_e32 v93, 0xffff0000, v50
	v_lshlrev_b32_e32 v94, 16, v51
	v_and_b32_e32 v95, 0xffff0000, v51
	v_lshlrev_b32_e32 v96, 16, v52
	v_and_b32_e32 v97, 0xffff0000, v52
	v_lshlrev_b32_e32 v98, 16, v53
	v_and_b32_e32 v99, 0xffff0000, v53
	v_lshlrev_b32_e32 v100, 16, v54
	v_and_b32_e32 v101, 0xffff0000, v54
	v_lshlrev_b32_e32 v102, 16, v55
	v_and_b32_e32 v103, 0xffff0000, v55
	v_lshlrev_b32_e32 v104, 16, v56
	v_and_b32_e32 v105, 0xffff0000, v56
	v_lshlrev_b32_e32 v106, 16, v57
	v_and_b32_e32 v107, 0xffff0000, v57
	v_pk_add_f32 v[140:141], v[76:77], 1.0 op_sel_hi:[1,0] neg_lo:[1,0] neg_hi:[1,0]
	v_pk_add_f32 v[142:143], v[78:79], 1.0 op_sel_hi:[1,0] neg_lo:[1,0] neg_hi:[1,0]
	v_pk_add_f32 v[226:227], v[80:81], 1.0 op_sel_hi:[1,0] neg_lo:[1,0] neg_hi:[1,0]
	v_pk_add_f32 v[228:229], v[82:83], 1.0 op_sel_hi:[1,0] neg_lo:[1,0] neg_hi:[1,0]
	v_pk_mul_f32 v[144:145], v[140:141], v[226:227]
	v_pk_mul_f32 v[146:147], v[142:143], v[228:229]
	v_pk_add_f32 v[230:231], v[84:85], 1.0 op_sel_hi:[1,0] neg_lo:[1,0] neg_hi:[1,0]
	v_pk_add_f32 v[232:233], v[86:87], 1.0 op_sel_hi:[1,0] neg_lo:[1,0] neg_hi:[1,0]
	v_pk_mul_f32 v[148:149], v[144:145], v[230:231]
	v_pk_mul_f32 v[150:151], v[146:147], v[232:233]
	v_pk_add_f32 v[234:235], v[88:89], 1.0 op_sel_hi:[1,0] neg_lo:[1,0] neg_hi:[1,0]
	v_pk_add_f32 v[236:237], v[90:91], 1.0 op_sel_hi:[1,0] neg_lo:[1,0] neg_hi:[1,0]
	v_pk_mul_f32 v[152:153], v[148:149], v[234:235]
	v_pk_mul_f32 v[154:155], v[150:151], v[236:237]
	v_pk_add_f32 v[238:239], v[92:93], 1.0 op_sel_hi:[1,0] neg_lo:[1,0] neg_hi:[1,0]
	v_pk_add_f32 v[240:241], v[94:95], 1.0 op_sel_hi:[1,0] neg_lo:[1,0] neg_hi:[1,0]
	v_pk_mul_f32 v[156:157], v[152:153], v[238:239]
	v_pk_mul_f32 v[158:159], v[154:155], v[240:241]
	v_pk_add_f32 v[242:243], v[96:97], 1.0 op_sel_hi:[1,0] neg_lo:[1,0] neg_hi:[1,0]
	v_pk_add_f32 v[244:245], v[98:99], 1.0 op_sel_hi:[1,0] neg_lo:[1,0] neg_hi:[1,0]
	v_pk_mul_f32 v[160:161], v[156:157], v[242:243]
	v_pk_mul_f32 v[162:163], v[158:159], v[244:245]
	v_pk_add_f32 v[246:247], v[100:101], 1.0 op_sel_hi:[1,0] neg_lo:[1,0] neg_hi:[1,0]
	v_pk_add_f32 v[248:249], v[102:103], 1.0 op_sel_hi:[1,0] neg_lo:[1,0] neg_hi:[1,0]
	v_pk_mul_f32 v[164:165], v[160:161], v[246:247]
	v_pk_mul_f32 v[166:167], v[162:163], v[248:249]
	v_pk_add_f32 v[74:75], v[104:105], 1.0 op_sel_hi:[1,0] neg_lo:[1,0] neg_hi:[1,0]
	v_pk_add_f32 v[172:173], v[106:107], 1.0 op_sel_hi:[1,0] neg_lo:[1,0] neg_hi:[1,0]
	v_pk_mul_f32 v[168:169], v[164:165], v[74:75]
	v_pk_mul_f32 v[170:171], v[166:167], v[172:173]
	s_waitcnt lgkmcnt(0)
	s_barrier
	s_add_i32 s17, s17, -1
	s_branch .Lhg_ploop
